# ssd_out main loop: gate loads and gated-output stores as one 16-byte access per lane (v_permlane16_swap pairs) instead of two 8-byte accesses
# speedup vs baseline: 1.0305x; 1.0065x over previous
; #define LAS __attribute__((address_space(3)))
; __device__ void phase_ssd_out(KP P, int layer, LAS unsigned char* lds) {
;     ...
;             for (int ltp = 0; ltp < 4; ++ltp) {
;                 u32x2 zv[2][2]; bf16x8 cf[2][2]; f32x4 acc[2][2]; float csl[2], dsk[2]; int lrow[2];
; #pragma unroll
;                 for (int u = 0; u < 2; ++u) { const int lt = 2 * ltp + u, l = lt * 16 + r; lrow[u] = l;
;                     zv[u][0] = *(const u32x2*)(zl + (long)lt * 16 * PW); zv[u][1] = *(const u32x2*)(zl + (long)lt * 16 * PW + 16);
;                     cf[u][0] = *(const LAS bf16x8*)(Cc + l * 72 + q * 8); cf[u][1] = *(const LAS bf16x8*)(Cc + l * 72 + 32 + q * 8);
;                     csl[u] = csw[l]; dsk[u] = Dh * __builtin_amdgcn_rcpf(dtw[l]); }
; #pragma unroll
;                 for (int u = 0; u < 2; ++u)
; #pragma unroll
;                     for (int pt2 = 0; pt2 < 2; ++pt2) { f32x4 a = (f32x4){0.f, 0.f, 0.f, 0.f};
;                         a = __builtin_amdgcn_mfma_f32_16x16x32_bf16(*(const LAS bf16x8*)(bpw + (pt2 * 2) * 1024), cf[u][0], a, 0, 0, 0); a = __builtin_amdgcn_mfma_f32_16x16x32_bf16(*(const LAS bf16x8*)(bpw + (pt2 * 2 + 1) * 1024), cf[u][1], a, 0, 0, 0);
;                         acc[u][pt2] = a * __expf(csl[u]); }
.LBB0_29:
	v_lshl_or_b32 v81, s23, 5, v155
	s_lshl_b32 s14, s23, 1
	s_waitcnt lgkmcnt(0)
	v_mad_u64_u32 v[0:1], s[12:13], v81, s80, v[158:159]
	s_mul_i32 s20, s23, 0x22000
	s_or_b32 s12, s14, 1
	v_lshl_add_u64 v[58:59], s[20:21], 1, v[52:53]
	s_mul_i32 s20, s12, 0x11000
	v_and_b32_e32 v62, 4, v156
	v_mul_u32_u24_e32 v62, 10, v62
	v_sub_u32_e32 v62, 40, v62
	v_mov_b32_e32 v63, 0
	v_lshl_add_u64 v[62:63], v[58:59], 0, v[62:63]
	global_load_dwordx4 v[60:63], v[62:63], off offset:2552
	ds_read_b128 v[20:23], v0 offset:18432
	ds_read_b128 v[16:19], v0 offset:18496
	v_lshl_add_u32 v79, v81, 2, v154
	v_lshl_add_u64 v[0:1], s[20:21], 1, v[52:53]
	ds_read2st64_b32 v[66:67], v79 offset0:144 offset1:160
	v_and_b32_e32 v56, 4, v156
	v_mul_u32_u24_e32 v56, 10, v56
	v_sub_u32_e32 v56, 40, v56
	v_mov_b32_e32 v57, 0
	v_lshl_add_u64 v[56:57], v[0:1], 0, v[56:57]
	global_load_dwordx4 v[54:57], v[56:57], off offset:2552
	v_lshl_or_b32 v80, s12, 4, v155
	v_mad_u64_u32 v[0:1], s[12:13], v80, s80, v[158:159]
	ds_read_b128 v[28:31], v0 offset:18432
	ds_read_b128 v[24:27], v0 offset:18496
	s_waitcnt lgkmcnt(2)
	v_mul_f32_e32 v0, 0x3fb8aa3b, v66
	v_exp_f32_e32 v40, v0
	ds_read_b128 v[0:3], v229
	ds_read_b128 v[32:35], v229 offset:1024
	s_waitcnt lgkmcnt(1)
	v_mfma_f32_16x16x32_bf16 v[4:7], v[0:3], v[20:23], 0
	ds_read_b128 v[36:39], v229 offset:3072
	v_lshl_add_u32 v78, v80, 2, v154
	ds_read2st64_b32 v[64:65], v78 offset0:144 offset1:160
	s_waitcnt lgkmcnt(2)
	v_mfma_f32_16x16x32_bf16 v[4:7], v[32:35], v[16:19], v[4:7]
	s_mov_b32 s14, 0
	s_cmp_eq_u32 s23, 0
	v_mfma_f32_16x16x32_bf16 v[0:3], v[0:3], v[28:31], 0
	v_mfma_f32_16x16x32_bf16 v[0:3], v[32:35], v[24:27], v[0:3]
	s_nop 3
	v_mul_f32_e64 v10, v40, v6
	v_mul_f32_e64 v11, v40, v7
	v_pk_mul_f32 v[8:9], v[40:41], v[4:5] op_sel_hi:[0,1]
	ds_read_b128 v[4:7], v229 offset:2048
	s_waitcnt lgkmcnt(0)
	v_mfma_f32_16x16x32_bf16 v[12:15], v[4:7], v[20:23], 0
	v_mfma_f32_16x16x32_bf16 v[12:15], v[36:39], v[16:19], v[12:15]
	v_mfma_f32_16x16x32_bf16 v[4:7], v[4:7], v[28:31], 0
	v_mfma_f32_16x16x32_bf16 v[4:7], v[36:39], v[24:27], v[4:7]
	s_nop 5
	v_mul_f32_e64 v14, v40, v14
	v_mul_f32_e64 v15, v40, v15
	v_pk_mul_f32 v[12:13], v[40:41], v[12:13] op_sel_hi:[0,1]
	v_mul_f32_e32 v40, 0x3fb8aa3b, v64
	v_exp_f32_e32 v40, v40
	s_nop 0
	v_pk_mul_f32 v[2:3], v[40:41], v[2:3] op_sel_hi:[0,1]
	v_pk_mul_f32 v[0:1], v[40:41], v[0:1] op_sel_hi:[0,1]
	v_pk_mul_f32 v[6:7], v[40:41], v[6:7] op_sel_hi:[0,1]
	v_pk_mul_f32 v[4:5], v[40:41], v[4:5] op_sel_hi:[0,1]
	s_cbranch_scc1 .LBB0_33
	s_mov_b32 s12, 0
	v_mov_b32_e32 v48, v203
	v_mov_b32_e32 v49, v202
	v_mov_b32_e32 v50, v201
	v_mov_b32_e32 v51, v200

; #define LAS __attribute__((address_space(3)))
; __device__ __forceinline__ unsigned cvt_pk_bf16(float lo, float hi) { unsigned r; asm volatile("v_cvt_pk_bf16_f32 %0, %1, %2" : "=v"(r) : "v"(lo), "v"(hi)); return r; }
; __device__ __forceinline__ float bflo(unsigned w) { return __uint_as_float(w << 16); }
; __device__ __forceinline__ float bfhi(unsigned w) { return __uint_as_float(w & 0xffff0000u); }
; __device__ void phase_ssd_out(KP P, int layer, LAS unsigned char* lds) {
;     ...
;                 for (int u = 0; u < 2; ++u) { const int lt = 2 * ltp + u; const f32x4 acc0 = acc[u][0], acc1 = acc[u][1]; const u32x2 z0 = zv[u][0], z1 = zv[u][1];
;                   float s0, s1, s2, s3, s4, s5, s6, s7;
;                   sigmoid2(bflo(z0.x), bfhi(z0.x), s0, s1); sigmoid2(bflo(z0.y), bfhi(z0.y), s2, s3); sigmoid2(bflo(z1.x), bfhi(z1.x), s4, s5); sigmoid2(bflo(z1.y), bfhi(z1.y), s6, s7);
;                   const float y0 = acc0[0] * bflo(z0.x) * s0, y1 = acc0[1] * bfhi(z0.x) * s1, y2 = acc0[2] * bflo(z0.y) * s2, y3 = acc0[3] * bfhi(z0.y) * s3;
;                   const float y4 = acc1[0] * bflo(z1.x) * s4, y5 = acc1[1] * bfhi(z1.x) * s5, y6 = acc1[2] * bflo(z1.y) * s6, y7 = acc1[3] * bfhi(z1.y) * s7;
;                   bf16_t* zp = zl + (long)lt * 16 * PW;
;                   u32x2 o0, o1; o0.x = cvt_pk_bf16(y0, y1); o0.y = cvt_pk_bf16(y2, y3); o1.x = cvt_pk_bf16(y4, y5); o1.y = cvt_pk_bf16(y6, y7);
;                   *(u32x2*)zp = o0; *(u32x2*)(zp + 16) = o1;
;                   float sq = (y0 * y0 + y1 * y1) + (y2 * y2 + y3 * y3) + (y4 * y4 + y5 * y5) + (y6 * y6 + y7 * y7);
;                   sq += __shfl_xor(sq, 16); sq += __shfl_xor(sq, 32);
;                   if (q == 0) { LAS float* rp = red + wid * 128 + lrow[u]; *rp = (ph == 0) ? sq : (*rp + sq); } }
.LBB0_41:
	v_cvt_pk_bf16_f32 v28, v8, v9
	v_cvt_pk_bf16_f32 v29, v44, v45
	v_cvt_pk_bf16_f32 v30, v10, v11
	v_cvt_pk_bf16_f32 v31, v46, v47
	s_waitcnt vmcnt(1)
	v_permlane16_swap_b32 v60, v62
	v_permlane16_swap_b32 v61, v63
	s_nop 1
	v_and_b32_e32 v34, 0xffff0000, v62
	v_mfma_f32_16x16x32_bf16 v[8:11], v[16:19], v[28:31], v[0:3]
	v_lshlrev_b32_e32 v17, 16, v63
	v_max_f32_e64 v16, -v17, -v17
	v_min_f32_e32 v16, 0x42200000, v16
	v_mfma_f32_16x16x32_bf16 v[0:3], v[20:23], v[28:31], v[4:7]
	v_and_b32_e32 v35, 0xffff0000, v63
	v_mul_f32_e32 v16, 0x3fb8aa3b, v16
	s_waitcnt vmcnt(1)
	v_lshlrev_b32_e32 v21, 16, v60
	v_lshlrev_b32_e32 v5, 16, v62
	v_max_f32_e64 v4, -v5, -v5
	v_min_f32_e32 v4, 0x42200000, v4
	v_mul_f32_e32 v4, 0x3fb8aa3b, v4
	v_exp_f32_e32 v6, v4
	v_max_f32_e64 v4, -v34, -v34
	v_min_f32_e32 v4, 0x42200000, v4
	v_mul_f32_e32 v4, 0x3fb8aa3b, v4
	v_exp_f32_e32 v7, v4
	v_exp_f32_e32 v18, v16
	v_max_f32_e64 v16, -v35, -v35
	v_max_f32_e64 v20, -v21, -v21
	v_min_f32_e32 v16, 0x42200000, v16
	v_min_f32_e32 v20, 0x42200000, v20
	v_mul_f32_e32 v16, 0x3fb8aa3b, v16
	v_and_b32_e32 v36, 0xffff0000, v60
	v_mul_f32_e32 v20, 0x3fb8aa3b, v20
	v_lshlrev_b32_e32 v29, 16, v61
	v_exp_f32_e32 v19, v16
	v_exp_f32_e32 v22, v20
	v_max_f32_e64 v20, -v36, -v36
	v_max_f32_e64 v28, -v29, -v29
	v_pk_add_f32 v[6:7], v[6:7], 1.0 op_sel_hi:[1,0]
	v_min_f32_e32 v20, 0x42200000, v20
	v_min_f32_e32 v28, 0x42200000, v28
	v_mul_f32_e32 v4, v6, v7
	v_mul_f32_e32 v20, 0x3fb8aa3b, v20
	v_and_b32_e32 v37, 0xffff0000, v61
	v_mul_f32_e32 v28, 0x3fb8aa3b, v28
	v_rcp_f32_e32 v4, v4
	v_exp_f32_e32 v23, v20
	v_exp_f32_e32 v30, v28
	v_max_f32_e64 v28, -v37, -v37
	v_pk_add_f32 v[18:19], v[18:19], 1.0 op_sel_hi:[1,0]
	v_min_f32_e32 v28, 0x42200000, v28
	v_mul_f32_e32 v16, v18, v19
	v_mul_f32_e32 v28, 0x3fb8aa3b, v28
	v_rcp_f32_e32 v16, v16
	v_exp_f32_e32 v31, v28
	v_mov_b32_e32 v32, v7
	v_mov_b32_e32 v33, v24
	v_pk_add_f32 v[22:23], v[22:23], 1.0 op_sel_hi:[1,0]
	v_pk_mul_f32 v[32:33], v[32:33], v[4:5]
	v_mov_b32_e32 v7, v25
	v_mov_b32_e32 v5, v34
	v_mul_f32_e32 v20, v22, v23
	v_pk_mul_f32 v[4:5], v[6:7], v[4:5]
	v_rcp_f32_e32 v20, v20
	v_mul_f32_e32 v25, v4, v5
	v_mov_b32_e32 v4, v19
	v_mov_b32_e32 v5, v26
	v_pk_add_f32 v[30:31], v[30:31], 1.0 op_sel_hi:[1,0]
	v_pk_mul_f32 v[4:5], v[4:5], v[16:17]
	v_mov_b32_e32 v19, v27
	v_mov_b32_e32 v17, v35
	v_mul_f32_e32 v28, v30, v31
	v_mul_f32_e32 v26, v4, v5
	v_pk_mul_f32 v[4:5], v[18:19], v[16:17]
	v_rcp_f32_e32 v28, v28
	v_mul_f32_e32 v16, v4, v5
	v_mov_b32_e32 v4, v23
	v_mov_b32_e32 v5, v12
	v_pk_mul_f32 v[4:5], v[4:5], v[20:21]
	v_mov_b32_e32 v23, v13
	v_mov_b32_e32 v21, v36
	v_mul_f32_e32 v12, v4, v5
	v_pk_mul_f32 v[4:5], v[22:23], v[20:21]
	v_mul_f32_e32 v24, v32, v33
	v_mul_f32_e32 v13, v4, v5
	v_mov_b32_e32 v4, v31
	v_mov_b32_e32 v5, v14
	v_pk_mul_f32 v[4:5], v[4:5], v[28:29]
	v_mov_b32_e32 v31, v15
	v_mov_b32_e32 v29, v37
	v_mul_f32_e32 v14, v4, v5
	v_pk_mul_f32 v[4:5], v[30:31], v[28:29]
	s_nop 0
	v_mul_f32_e32 v15, v4, v5
	v_cvt_pk_bf16_f32 v4, v24, v25
	v_cvt_pk_bf16_f32 v5, v26, v16
	v_cvt_pk_bf16_f32 v6, v12, v13
	v_cvt_pk_bf16_f32 v7, v14, v15
	v_and_b32_e32 v30, 4, v156
	v_mul_u32_u24_e32 v30, 6, v30
	v_mov_b32_e32 v31, 0
	v_permlane16_swap_b32 v4, v6
	v_permlane16_swap_b32 v5, v7
	v_lshl_add_u64 v[30:31], v[58:59], 0, v[30:31]
	global_store_dwordx4 v[30:31], v[4:7], off offset:2560
	s_nop 1
	v_mul_f32_e32 v4, v26, v26
	v_mul_f32_e32 v5, v24, v24
	v_fmac_f32_e32 v4, v16, v16
	v_fmac_f32_e32 v5, v25, v25
	v_add_f32_e32 v4, v5, v4
	v_mul_f32_e32 v5, v12, v12
	v_fmac_f32_e32 v5, v13, v13
	v_add_f32_e32 v4, v4, v5
	v_mul_f32_e32 v5, v14, v14
	v_fmac_f32_e32 v5, v15, v15
	v_add_f32_e32 v4, v5, v4
	ds_bpermute_b32 v5, v193, v4
	s_waitcnt lgkmcnt(0)
	v_add_f32_e32 v4, v4, v5
	ds_bpermute_b32 v5, v194, v4
	s_and_saveexec_b64 s[12:13], s[40:41]
	s_cbranch_execz .LBB0_45
	s_andn2_b64 vcc, exec, s[10:11]
	s_waitcnt lgkmcnt(0)
	v_add_f32_e32 v4, v4, v5
	s_cbranch_vccnz .LBB0_44
	ds_read_b32 v5, v79 offset:45056
	s_waitcnt lgkmcnt(0)
	v_add_f32_e32 v4, v4, v5

; #define LAS __attribute__((address_space(3)))
; __device__ __forceinline__ unsigned cvt_pk_bf16(float lo, float hi) { unsigned r; asm volatile("v_cvt_pk_bf16_f32 %0, %1, %2" : "=v"(r) : "v"(lo), "v"(hi)); return r; }
; __device__ __forceinline__ float bflo(unsigned w) { return __uint_as_float(w << 16); }
; __device__ __forceinline__ float bfhi(unsigned w) { return __uint_as_float(w & 0xffff0000u); }
; __device__ void phase_ssd_out(KP P, int layer, LAS unsigned char* lds) {
;     ...
;                 for (int u = 0; u < 2; ++u) { const int lt = 2 * ltp + u; const f32x4 acc0 = acc[u][0], acc1 = acc[u][1]; const u32x2 z0 = zv[u][0], z1 = zv[u][1];
;                   float s0, s1, s2, s3, s4, s5, s6, s7;
;                   sigmoid2(bflo(z0.x), bfhi(z0.x), s0, s1); sigmoid2(bflo(z0.y), bfhi(z0.y), s2, s3); sigmoid2(bflo(z1.x), bfhi(z1.x), s4, s5); sigmoid2(bflo(z1.y), bfhi(z1.y), s6, s7);
;                   const float y0 = acc0[0] * bflo(z0.x) * s0, y1 = acc0[1] * bfhi(z0.x) * s1, y2 = acc0[2] * bflo(z0.y) * s2, y3 = acc0[3] * bfhi(z0.y) * s3;
;                   const float y4 = acc1[0] * bflo(z1.x) * s4, y5 = acc1[1] * bfhi(z1.x) * s5, y6 = acc1[2] * bflo(z1.y) * s6, y7 = acc1[3] * bfhi(z1.y) * s7;
;                   bf16_t* zp = zl + (long)lt * 16 * PW;
;                   u32x2 o0, o1; o0.x = cvt_pk_bf16(y0, y1); o0.y = cvt_pk_bf16(y2, y3); o1.x = cvt_pk_bf16(y4, y5); o1.y = cvt_pk_bf16(y6, y7);
;                   *(u32x2*)zp = o0; *(u32x2*)(zp + 16) = o1;
;                   float sq = (y0 * y0 + y1 * y1) + (y2 * y2 + y3 * y3) + (y4 * y4 + y5 * y5) + (y6 * y6 + y7 * y7);
;                   sq += __shfl_xor(sq, 16); sq += __shfl_xor(sq, 32);
;                   if (q == 0) { LAS float* rp = red + wid * 128 + lrow[u]; *rp = (ph == 0) ? sq : (*rp + sq); } }
.LBB0_45:
	s_or_b64 exec, exec, s[12:13]
	s_waitcnt vmcnt(1) lgkmcnt(0)
	v_permlane16_swap_b32 v54, v56
	v_permlane16_swap_b32 v55, v57
	s_nop 1
	v_lshlrev_b32_e32 v5, 16, v56
	v_max_f32_e64 v4, -v5, -v5
	v_min_f32_e32 v4, 0x42200000, v4
	v_and_b32_e32 v26, 0xffff0000, v56
	v_mul_f32_e32 v4, 0x3fb8aa3b, v4
	v_exp_f32_e32 v6, v4
	v_max_f32_e64 v4, -v26, -v26
	v_min_f32_e32 v4, 0x42200000, v4
	v_mul_f32_e32 v4, 0x3fb8aa3b, v4
	v_lshlrev_b32_e32 v13, 16, v57
	s_waitcnt vmcnt(1)
	v_lshlrev_b32_e32 v17, 16, v54
	v_exp_f32_e32 v7, v4
	v_max_f32_e64 v4, -v13, -v13
	v_max_f32_e64 v16, -v17, -v17
	v_min_f32_e32 v4, 0x42200000, v4
	v_min_f32_e32 v16, 0x42200000, v16
	v_and_b32_e32 v27, 0xffff0000, v57
	v_mul_f32_e32 v4, 0x3fb8aa3b, v4
	v_and_b32_e32 v28, 0xffff0000, v54
	v_mul_f32_e32 v16, 0x3fb8aa3b, v16
	v_exp_f32_e32 v14, v4
	v_max_f32_e64 v4, -v27, -v27
	v_exp_f32_e32 v18, v16
	v_max_f32_e64 v16, -v28, -v28
	v_min_f32_e32 v4, 0x42200000, v4
	v_min_f32_e32 v16, 0x42200000, v16
	v_mul_f32_e32 v4, 0x3fb8aa3b, v4
	v_mul_f32_e32 v16, 0x3fb8aa3b, v16
	v_lshlrev_b32_e32 v21, 16, v55
	v_exp_f32_e32 v15, v4
	v_exp_f32_e32 v19, v16
	v_max_f32_e64 v16, -v21, -v21
	v_pk_add_f32 v[6:7], v[6:7], 1.0 op_sel_hi:[1,0]
	v_min_f32_e32 v16, 0x42200000, v16
	v_mul_f32_e32 v4, v6, v7
	v_and_b32_e32 v29, 0xffff0000, v55
	v_mul_f32_e32 v16, 0x3fb8aa3b, v16
	v_rcp_f32_e32 v4, v4
	v_exp_f32_e32 v22, v16
	v_max_f32_e64 v16, -v29, -v29
	v_pk_add_f32 v[14:15], v[14:15], 1.0 op_sel_hi:[1,0]
	v_min_f32_e32 v16, 0x42200000, v16
	v_mul_f32_e32 v12, v14, v15
	v_mul_f32_e32 v16, 0x3fb8aa3b, v16
	v_rcp_f32_e32 v12, v12
	v_exp_f32_e32 v23, v16
	v_mov_b32_e32 v24, v7
	v_mov_b32_e32 v25, v8
	v_pk_add_f32 v[18:19], v[18:19], 1.0 op_sel_hi:[1,0]
	v_pk_mul_f32 v[24:25], v[24:25], v[4:5]
	v_mov_b32_e32 v7, v9
	v_mov_b32_e32 v5, v26
	v_mul_f32_e32 v16, v18, v19
	v_pk_mul_f32 v[4:5], v[6:7], v[4:5]
	v_rcp_f32_e32 v16, v16
	v_mul_f32_e32 v6, v4, v5
	v_mov_b32_e32 v4, v15
	v_mov_b32_e32 v5, v10
	v_pk_add_f32 v[22:23], v[22:23], 1.0 op_sel_hi:[1,0]
	v_pk_mul_f32 v[4:5], v[4:5], v[12:13]
	v_mov_b32_e32 v15, v11
	v_mov_b32_e32 v13, v27
	v_mul_f32_e32 v20, v22, v23
	v_mul_f32_e32 v7, v4, v5
	v_pk_mul_f32 v[4:5], v[14:15], v[12:13]
	v_rcp_f32_e32 v20, v20
	v_mul_f32_e32 v9, v4, v5
	v_mov_b32_e32 v4, v19
	v_mov_b32_e32 v5, v0
	v_pk_mul_f32 v[4:5], v[4:5], v[16:17]
	v_mov_b32_e32 v19, v1
	v_mov_b32_e32 v17, v28
	v_pk_mul_f32 v[0:1], v[18:19], v[16:17]
	v_mul_f32_e32 v4, v4, v5
	v_mul_f32_e32 v5, v0, v1
	v_mov_b32_e32 v0, v23
	v_mov_b32_e32 v1, v2
	v_pk_mul_f32 v[0:1], v[0:1], v[20:21]
	v_mov_b32_e32 v23, v3
	v_mov_b32_e32 v21, v29
	v_mul_f32_e32 v8, v24, v25
	v_mul_f32_e32 v10, v0, v1
	v_pk_mul_f32 v[0:1], v[22:23], v[20:21]
	v_mul_f32_e32 v2, v8, v8
	v_mul_f32_e32 v0, v0, v1
	v_mul_f32_e32 v1, v7, v7
	v_fmac_f32_e32 v1, v9, v9
	v_fmac_f32_e32 v2, v6, v6
	v_add_f32_e32 v1, v2, v1
	v_mul_f32_e32 v2, v4, v4
	v_fmac_f32_e32 v2, v5, v5
	v_add_f32_e32 v1, v1, v2
	v_mul_f32_e32 v2, v10, v10
	v_fmac_f32_e32 v2, v0, v0
	v_add_f32_e32 v1, v2, v1
	ds_bpermute_b32 v11, v193, v1
	v_cvt_pk_bf16_f32 v2, v8, v6
	v_cvt_pk_bf16_f32 v3, v7, v9
	v_cvt_pk_bf16_f32 v4, v4, v5
	v_cvt_pk_bf16_f32 v5, v10, v0
	s_waitcnt lgkmcnt(0)
	v_add_f32_e32 v0, v1, v11
	ds_bpermute_b32 v1, v194, v0
	v_add_co_u32_e32 v6, vcc, s77, v68
	s_nop 1
	v_addc_co_u32_e32 v7, vcc, 0, v69, vcc
	v_and_b32_e32 v11, 4, v156
	v_mul_u32_u24_e32 v11, 6, v11
	v_permlane16_swap_b32 v2, v4
	v_permlane16_swap_b32 v3, v5
	v_add_co_u32_e32 v6, vcc, v6, v11
	s_nop 1
	v_addc_co_u32_e32 v7, vcc, 0, v7, vcc
	global_store_dwordx4 v[6:7], v[2:5], off
	s_nop 1
	s_and_saveexec_b64 s[12:13], s[40:41]
	s_cbranch_execz .LBB0_28
	s_andn2_b64 vcc, exec, s[10:11]
	s_waitcnt lgkmcnt(0)
	v_add_f32_e32 v0, v0, v1
	s_cbranch_vccnz .LBB0_27
	ds_read_b32 v1, v78 offset:45056
	s_waitcnt lgkmcnt(0)
	v_add_f32_e32 v0, v0, v1
	s_branch .LBB0_27
